# same as previous sample_gemm version plus 64-byte alignment of the main GEMM loop header
# baseline (speedup 1.0000x reference)
.LBB0_743:
	s_add_u32 s8, s8, 0x80
	s_addc_u32 s9, s9, 0
	s_add_u32 s27, s34, 0x100
	v_mov_b32_e32 v2, 0
	s_addc_u32 s34, s35, 0
	s_mov_b32 s10, 0
	v_mov_b32_e32 v3, v2
	v_mov_b32_e32 v4, v2
	v_mov_b32_e32 v5, v2
	v_mov_b32_e32 v6, v2
	v_mov_b32_e32 v7, v2
	v_mov_b32_e32 v8, v2
	v_mov_b32_e32 v9, v2
	v_mov_b32_e32 v18, v2
	v_mov_b32_e32 v19, v2
	v_mov_b32_e32 v20, v2
	v_mov_b32_e32 v21, v2
	v_mov_b32_e32 v22, v2
	v_mov_b32_e32 v23, v2
	v_mov_b32_e32 v24, v2
	v_mov_b32_e32 v25, v2
	v_mov_b32_e32 v34, v2
	v_mov_b32_e32 v35, v2
	v_mov_b32_e32 v36, v2
	v_mov_b32_e32 v37, v2
	v_mov_b32_e32 v38, v2
	v_mov_b32_e32 v39, v2
	v_mov_b32_e32 v40, v2
	v_mov_b32_e32 v41, v2
	v_mov_b32_e32 v50, v2
	v_mov_b32_e32 v51, v2
	v_mov_b32_e32 v52, v2
	v_mov_b32_e32 v53, v2
	v_mov_b32_e32 v54, v2
	v_mov_b32_e32 v55, v2
	v_mov_b32_e32 v56, v2
	v_mov_b32_e32 v57, v2
	v_mov_b32_e32 v10, v2
	v_mov_b32_e32 v11, v2
	v_mov_b32_e32 v12, v2
	v_mov_b32_e32 v13, v2
	v_mov_b32_e32 v14, v2
	v_mov_b32_e32 v15, v2
	v_mov_b32_e32 v16, v2
	v_mov_b32_e32 v17, v2
	v_mov_b32_e32 v26, v2
	v_mov_b32_e32 v27, v2
	v_mov_b32_e32 v28, v2
	v_mov_b32_e32 v29, v2
	v_mov_b32_e32 v30, v2
	v_mov_b32_e32 v31, v2
	v_mov_b32_e32 v32, v2
	v_mov_b32_e32 v33, v2
	v_mov_b32_e32 v42, v2
	v_mov_b32_e32 v43, v2
	v_mov_b32_e32 v44, v2
	v_mov_b32_e32 v45, v2
	v_mov_b32_e32 v46, v2
	v_mov_b32_e32 v47, v2
	v_mov_b32_e32 v48, v2
	v_mov_b32_e32 v49, v2
	v_mov_b32_e32 v58, v2
	v_mov_b32_e32 v59, v2
	v_mov_b32_e32 v60, v2
	v_mov_b32_e32 v61, v2
	v_mov_b32_e32 v62, v2
	v_mov_b32_e32 v63, v2
	v_mov_b32_e32 v64, v2
	v_mov_b32_e32 v65, v2
	v_mov_b32_e32 v66, v2
	v_mov_b32_e32 v67, v2
	v_mov_b32_e32 v68, v2
	v_mov_b32_e32 v69, v2
	v_mov_b32_e32 v70, v2
	v_mov_b32_e32 v71, v2
	v_mov_b32_e32 v72, v2
	v_mov_b32_e32 v73, v2
	v_mov_b32_e32 v82, v2
	v_mov_b32_e32 v83, v2
	v_mov_b32_e32 v84, v2
	v_mov_b32_e32 v85, v2
	v_mov_b32_e32 v86, v2
	v_mov_b32_e32 v87, v2
	v_mov_b32_e32 v88, v2
	v_mov_b32_e32 v89, v2
	v_mov_b32_e32 v98, v2
	v_mov_b32_e32 v99, v2
	v_mov_b32_e32 v100, v2
	v_mov_b32_e32 v101, v2
	v_mov_b32_e32 v102, v2
	v_mov_b32_e32 v103, v2
	v_mov_b32_e32 v104, v2
	v_mov_b32_e32 v105, v2
	v_mov_b32_e32 v114, v2
	v_mov_b32_e32 v115, v2
	v_mov_b32_e32 v116, v2
	v_mov_b32_e32 v117, v2
	v_mov_b32_e32 v118, v2
	v_mov_b32_e32 v119, v2
	v_mov_b32_e32 v120, v2
	v_mov_b32_e32 v121, v2
	v_mov_b32_e32 v74, v2
	v_mov_b32_e32 v75, v2
	v_mov_b32_e32 v76, v2
	v_mov_b32_e32 v77, v2
	v_mov_b32_e32 v78, v2
	v_mov_b32_e32 v79, v2
	v_mov_b32_e32 v80, v2
	v_mov_b32_e32 v81, v2
	v_mov_b32_e32 v90, v2
	v_mov_b32_e32 v91, v2
	v_mov_b32_e32 v92, v2
	v_mov_b32_e32 v93, v2
	v_mov_b32_e32 v94, v2
	v_mov_b32_e32 v95, v2
	v_mov_b32_e32 v96, v2
	v_mov_b32_e32 v97, v2
	v_mov_b32_e32 v106, v2
	v_mov_b32_e32 v107, v2
	v_mov_b32_e32 v108, v2
	v_mov_b32_e32 v109, v2
	v_mov_b32_e32 v110, v2
	v_mov_b32_e32 v111, v2
	v_mov_b32_e32 v112, v2
	v_mov_b32_e32 v113, v2
	v_mov_b32_e32 v122, v2
	v_mov_b32_e32 v123, v2
	v_mov_b32_e32 v124, v2
	v_mov_b32_e32 v125, v2
	v_mov_b32_e32 v126, v2
	v_mov_b32_e32 v127, v2
	v_mov_b32_e32 v128, v2
	v_mov_b32_e32 v129, v2
	.p2align	6
